# out-projection epilogue rewritten by hand: residual-tile loads of each half issued up front (second half into freed accumulators), no load waits behind earlier stores/atomics, one reduction pass for t
# speedup vs baseline: 1.0029x; 1.0029x over previous
.LBB0_1029:
	s_ashr_i32 s21, s28, 4
	s_mul_hi_i32 s23, s21, 0x9000
	s_mul_i32 s21, s21, 0x9000
	s_add_u32 s98, s44, s21
	s_addc_u32 s99, s45, s23
	s_add_u32 s100, s46, s21
	s_addc_u32 s101, s47, s23
	v_lshl_or_b32 v252, s30, 8, v186
	v_lshl_add_u32 v253, s28, 8, v184
	v_lshlrev_b32_e32 v191, 2, v252
	v_lshlrev_b32_e32 v245, 2, v253
	v_lshlrev_b32_e32 v252, 1, v252
	v_lshl_add_u32 v132, v253, 11, v252
	v_add_u32_e32 v133, 0x8000, v132
	v_add_u32_e32 v134, 0x10000, v132
	v_add_u32_e32 v135, 0x18000, v132
	global_load_dwordx4 v[152:155], v191, s[98:99] offset:0
	global_load_dwordx4 v[156:159], v191, s[98:99] offset:16
	global_load_dwordx4 v[160:163], v191, s[98:99] offset:512
	global_load_dwordx4 v[164:167], v191, s[98:99] offset:528
	global_load_dwordx4 v[168:171], v191, s[12:13] offset:0
	global_load_dwordx4 v[172:175], v191, s[12:13] offset:16
	global_load_dwordx4 v[176:179], v191, s[12:13] offset:512
	global_load_dwordx4 v[180:183], v191, s[12:13] offset:528
	global_load_dwordx4 v[192:195], v191, s[100:101] offset:0
	global_load_dwordx4 v[196:199], v191, s[100:101] offset:16
	global_load_dwordx4 v[200:203], v191, s[100:101] offset:512
	global_load_dwordx4 v[204:207], v191, s[100:101] offset:528
	global_load_dwordx4 v[208:211], v132, s[80:81]
	global_load_dwordx4 v[212:215], v132, s[80:81] offset:256
	global_load_dwordx4 v[216:219], v133, s[80:81]
	global_load_dwordx4 v[220:223], v133, s[80:81] offset:256
	global_load_dwordx4 v[224:227], v134, s[80:81]
	global_load_dwordx4 v[228:231], v134, s[80:81] offset:256
	global_load_dwordx4 v[232:235], v135, s[80:81]
	global_load_dwordx4 v[128:131], v135, s[80:81] offset:256
	s_waitcnt vmcnt(8)
	v_add_f32_e32 v152, 1.0, v152
	v_add_f32_e32 v153, 1.0, v153
	v_add_f32_e32 v154, 1.0, v154
	v_add_f32_e32 v155, 1.0, v155
	v_add_f32_e32 v156, 1.0, v156
	v_add_f32_e32 v157, 1.0, v157
	v_add_f32_e32 v158, 1.0, v158
	v_add_f32_e32 v159, 1.0, v159
	v_add_f32_e32 v160, 1.0, v160
	v_add_f32_e32 v161, 1.0, v161
	v_add_f32_e32 v162, 1.0, v162
	v_add_f32_e32 v163, 1.0, v163
	v_add_f32_e32 v164, 1.0, v164
	v_add_f32_e32 v165, 1.0, v165
	v_add_f32_e32 v166, 1.0, v166
	v_add_f32_e32 v167, 1.0, v167
	v_add_f32_e32 v192, 1.0, v192
	v_add_f32_e32 v193, 1.0, v193
	v_add_f32_e32 v194, 1.0, v194
	v_add_f32_e32 v195, 1.0, v195
	v_add_f32_e32 v196, 1.0, v196
	v_add_f32_e32 v197, 1.0, v197
	v_add_f32_e32 v198, 1.0, v198
	v_add_f32_e32 v199, 1.0, v199
	v_add_f32_e32 v200, 1.0, v200
	v_add_f32_e32 v201, 1.0, v201
	v_add_f32_e32 v202, 1.0, v202
	v_add_f32_e32 v203, 1.0, v203
	v_add_f32_e32 v204, 1.0, v204
	v_add_f32_e32 v205, 1.0, v205
	v_add_f32_e32 v206, 1.0, v206
	v_add_f32_e32 v207, 1.0, v207
	v_mul_f32_e32 v168, v168, v192
	v_mul_f32_e32 v169, v169, v193
	v_mul_f32_e32 v170, v170, v194
	v_mul_f32_e32 v171, v171, v195
	v_mul_f32_e32 v172, v172, v196
	v_mul_f32_e32 v173, v173, v197
	v_mul_f32_e32 v174, v174, v198
	v_mul_f32_e32 v175, v175, v199
	v_mul_f32_e32 v176, v176, v200
	v_mul_f32_e32 v177, v177, v201
	v_mul_f32_e32 v178, v178, v202
	v_mul_f32_e32 v179, v179, v203
	v_mul_f32_e32 v180, v180, v204
	v_mul_f32_e32 v181, v181, v205
	v_mul_f32_e32 v182, v182, v206
	v_mul_f32_e32 v183, v183, v207
	s_waitcnt vmcnt(7)
	v_lshlrev_b32_e32 v192, 16, v208
	v_and_b32_e32 v193, 0xffff0000, v208
	v_lshlrev_b32_e32 v194, 16, v209
	v_and_b32_e32 v195, 0xffff0000, v209
	v_lshlrev_b32_e32 v196, 16, v210
	v_and_b32_e32 v197, 0xffff0000, v210
	v_lshlrev_b32_e32 v198, 16, v211
	v_and_b32_e32 v199, 0xffff0000, v211
	v_fmac_f32_e32 v192, v152, v124
	v_fmac_f32_e32 v193, v153, v125
	v_fmac_f32_e32 v194, v154, v126
	v_fmac_f32_e32 v195, v155, v127
	v_fmac_f32_e32 v196, v156, v120
	v_fmac_f32_e32 v197, v157, v121
	v_fmac_f32_e32 v198, v158, v122
	v_fmac_f32_e32 v199, v159, v123
	v_cvt_pk_bf16_f32 v248, v192, v193
	v_cvt_pk_bf16_f32 v249, v194, v195
	v_cvt_pk_bf16_f32 v250, v196, v197
	v_cvt_pk_bf16_f32 v251, v198, v199
	global_store_dwordx4 v132, v[248:251], s[94:95]
	v_mul_f32_e32 v200, v192, v168
	v_mul_f32_e32 v201, v193, v169
	v_mul_f32_e32 v202, v194, v170
	v_mul_f32_e32 v203, v195, v171
	v_mul_f32_e32 v204, v196, v172
	v_mul_f32_e32 v205, v197, v173
	v_mul_f32_e32 v206, v198, v174
	v_mul_f32_e32 v207, v199, v175
	v_mul_f32_e32 v237, v192, v192
	v_fmac_f32_e32 v237, v193, v193
	v_fmac_f32_e32 v237, v194, v194
	v_fmac_f32_e32 v237, v195, v195
	v_fmac_f32_e32 v237, v196, v196
	v_fmac_f32_e32 v237, v197, v197
	v_fmac_f32_e32 v237, v198, v198
	v_fmac_f32_e32 v237, v199, v199
	v_cvt_pk_bf16_f32 v200, v200, v201
	v_cvt_pk_bf16_f32 v201, v202, v203
	v_cvt_pk_bf16_f32 v202, v204, v205
	v_cvt_pk_bf16_f32 v203, v206, v207
	global_store_dwordx4 v132, v[200:203], s[10:11]
	s_waitcnt vmcnt(8)
	v_lshlrev_b32_e32 v192, 16, v212
	v_and_b32_e32 v193, 0xffff0000, v212
	v_lshlrev_b32_e32 v194, 16, v213
	v_and_b32_e32 v195, 0xffff0000, v213
	v_lshlrev_b32_e32 v196, 16, v214
	v_and_b32_e32 v197, 0xffff0000, v214
	v_lshlrev_b32_e32 v198, 16, v215
	v_and_b32_e32 v199, 0xffff0000, v215
	v_fmac_f32_e32 v192, v160, v116
	v_fmac_f32_e32 v193, v161, v117
	v_fmac_f32_e32 v194, v162, v118
	v_fmac_f32_e32 v195, v163, v119
	v_fmac_f32_e32 v196, v164, v112
	v_fmac_f32_e32 v197, v165, v113
	v_fmac_f32_e32 v198, v166, v114
	v_fmac_f32_e32 v199, v167, v115
	v_cvt_pk_bf16_f32 v248, v192, v193
	v_cvt_pk_bf16_f32 v249, v194, v195
	v_cvt_pk_bf16_f32 v250, v196, v197
	v_cvt_pk_bf16_f32 v251, v198, v199
	global_store_dwordx4 v132, v[248:251], s[94:95] offset:256
	v_mul_f32_e32 v200, v192, v176
	v_mul_f32_e32 v201, v193, v177
	v_mul_f32_e32 v202, v194, v178
	v_mul_f32_e32 v203, v195, v179
	v_mul_f32_e32 v204, v196, v180
	v_mul_f32_e32 v205, v197, v181
	v_mul_f32_e32 v206, v198, v182
	v_mul_f32_e32 v207, v199, v183
	v_fmac_f32_e32 v237, v192, v192
	v_fmac_f32_e32 v237, v193, v193
	v_fmac_f32_e32 v237, v194, v194
	v_fmac_f32_e32 v237, v195, v195
	v_fmac_f32_e32 v237, v196, v196
	v_fmac_f32_e32 v237, v197, v197
	v_fmac_f32_e32 v237, v198, v198
	v_fmac_f32_e32 v237, v199, v199
	v_cvt_pk_bf16_f32 v200, v200, v201
	v_cvt_pk_bf16_f32 v201, v202, v203
	v_cvt_pk_bf16_f32 v202, v204, v205
	v_cvt_pk_bf16_f32 v203, v206, v207
	global_store_dwordx4 v132, v[200:203], s[10:11] offset:256
	v_add_u32_e32 v252, 0x40000, v132
	global_load_dwordx4 v[124:127], v252, s[80:81]
	global_load_dwordx4 v[120:123], v252, s[80:81] offset:256
	v_add_u32_e32 v252, 0x40000, v133
	global_load_dwordx4 v[116:119], v252, s[80:81]
	global_load_dwordx4 v[112:115], v252, s[80:81] offset:256
	s_waitcnt vmcnt(13)
	v_lshlrev_b32_e32 v192, 16, v216
	v_and_b32_e32 v193, 0xffff0000, v216
	v_lshlrev_b32_e32 v194, 16, v217
	v_and_b32_e32 v195, 0xffff0000, v217
	v_lshlrev_b32_e32 v196, 16, v218
	v_and_b32_e32 v197, 0xffff0000, v218
	v_lshlrev_b32_e32 v198, 16, v219
	v_and_b32_e32 v199, 0xffff0000, v219
	v_fmac_f32_e32 v192, v152, v108
	v_fmac_f32_e32 v193, v153, v109
	v_fmac_f32_e32 v194, v154, v110
	v_fmac_f32_e32 v195, v155, v111
	v_fmac_f32_e32 v196, v156, v104
	v_fmac_f32_e32 v197, v157, v105
	v_fmac_f32_e32 v198, v158, v106
	v_fmac_f32_e32 v199, v159, v107
	v_cvt_pk_bf16_f32 v248, v192, v193
	v_cvt_pk_bf16_f32 v249, v194, v195
	v_cvt_pk_bf16_f32 v250, v196, v197
	v_cvt_pk_bf16_f32 v251, v198, v199
	global_store_dwordx4 v133, v[248:251], s[94:95]
	v_mul_f32_e32 v200, v192, v168
	v_mul_f32_e32 v201, v193, v169
	v_mul_f32_e32 v202, v194, v170
	v_mul_f32_e32 v203, v195, v171
	v_mul_f32_e32 v204, v196, v172
	v_mul_f32_e32 v205, v197, v173
	v_mul_f32_e32 v206, v198, v174
	v_mul_f32_e32 v207, v199, v175
	v_mul_f32_e32 v238, v192, v192
	v_fmac_f32_e32 v238, v193, v193
	v_fmac_f32_e32 v238, v194, v194
	v_fmac_f32_e32 v238, v195, v195
	v_fmac_f32_e32 v238, v196, v196
	v_fmac_f32_e32 v238, v197, v197
	v_fmac_f32_e32 v238, v198, v198
	v_fmac_f32_e32 v238, v199, v199
	v_cvt_pk_bf16_f32 v200, v200, v201
	v_cvt_pk_bf16_f32 v201, v202, v203
	v_cvt_pk_bf16_f32 v202, v204, v205
	v_cvt_pk_bf16_f32 v203, v206, v207
	global_store_dwordx4 v133, v[200:203], s[10:11]
	s_waitcnt vmcnt(14)
	v_lshlrev_b32_e32 v192, 16, v220
	v_and_b32_e32 v193, 0xffff0000, v220
	v_lshlrev_b32_e32 v194, 16, v221
	v_and_b32_e32 v195, 0xffff0000, v221
	v_lshlrev_b32_e32 v196, 16, v222
	v_and_b32_e32 v197, 0xffff0000, v222
	v_lshlrev_b32_e32 v198, 16, v223
	v_and_b32_e32 v199, 0xffff0000, v223
	v_fmac_f32_e32 v192, v160, v100
	v_fmac_f32_e32 v193, v161, v101
	v_fmac_f32_e32 v194, v162, v102
	v_fmac_f32_e32 v195, v163, v103
	v_fmac_f32_e32 v196, v164, v96
	v_fmac_f32_e32 v197, v165, v97
	v_fmac_f32_e32 v198, v166, v98
	v_fmac_f32_e32 v199, v167, v99
	v_cvt_pk_bf16_f32 v248, v192, v193
	v_cvt_pk_bf16_f32 v249, v194, v195
	v_cvt_pk_bf16_f32 v250, v196, v197
	v_cvt_pk_bf16_f32 v251, v198, v199
	global_store_dwordx4 v133, v[248:251], s[94:95] offset:256
	v_mul_f32_e32 v200, v192, v176
	v_mul_f32_e32 v201, v193, v177
	v_mul_f32_e32 v202, v194, v178
	v_mul_f32_e32 v203, v195, v179
	v_mul_f32_e32 v204, v196, v180
	v_mul_f32_e32 v205, v197, v181
	v_mul_f32_e32 v206, v198, v182
	v_mul_f32_e32 v207, v199, v183
	v_fmac_f32_e32 v238, v192, v192
	v_fmac_f32_e32 v238, v193, v193
	v_fmac_f32_e32 v238, v194, v194
	v_fmac_f32_e32 v238, v195, v195
	v_fmac_f32_e32 v238, v196, v196
	v_fmac_f32_e32 v238, v197, v197
	v_fmac_f32_e32 v238, v198, v198
	v_fmac_f32_e32 v238, v199, v199
	v_cvt_pk_bf16_f32 v200, v200, v201
	v_cvt_pk_bf16_f32 v201, v202, v203
	v_cvt_pk_bf16_f32 v202, v204, v205
	v_cvt_pk_bf16_f32 v203, v206, v207
	global_store_dwordx4 v133, v[200:203], s[10:11] offset:256
	v_add_u32_e32 v252, 0x40000, v134
	global_load_dwordx4 v[108:111], v252, s[80:81]
	global_load_dwordx4 v[104:107], v252, s[80:81] offset:256
	v_add_u32_e32 v252, 0x40000, v135
	global_load_dwordx4 v[100:103], v252, s[80:81]
	global_load_dwordx4 v[96:99], v252, s[80:81] offset:256
	s_waitcnt vmcnt(19)
	v_lshlrev_b32_e32 v192, 16, v224
	v_and_b32_e32 v193, 0xffff0000, v224
	v_lshlrev_b32_e32 v194, 16, v225
	v_and_b32_e32 v195, 0xffff0000, v225
	v_lshlrev_b32_e32 v196, 16, v226
	v_and_b32_e32 v197, 0xffff0000, v226
	v_lshlrev_b32_e32 v198, 16, v227
	v_and_b32_e32 v199, 0xffff0000, v227
	v_fmac_f32_e32 v192, v152, v92
	v_fmac_f32_e32 v193, v153, v93
	v_fmac_f32_e32 v194, v154, v94
	v_fmac_f32_e32 v195, v155, v95
	v_fmac_f32_e32 v196, v156, v88
	v_fmac_f32_e32 v197, v157, v89
	v_fmac_f32_e32 v198, v158, v90
	v_fmac_f32_e32 v199, v159, v91
	v_cvt_pk_bf16_f32 v248, v192, v193
	v_cvt_pk_bf16_f32 v249, v194, v195
	v_cvt_pk_bf16_f32 v250, v196, v197
	v_cvt_pk_bf16_f32 v251, v198, v199
	global_store_dwordx4 v134, v[248:251], s[94:95]
	v_mul_f32_e32 v200, v192, v168
	v_mul_f32_e32 v201, v193, v169
	v_mul_f32_e32 v202, v194, v170
	v_mul_f32_e32 v203, v195, v171
	v_mul_f32_e32 v204, v196, v172
	v_mul_f32_e32 v205, v197, v173
	v_mul_f32_e32 v206, v198, v174
	v_mul_f32_e32 v207, v199, v175
	v_mul_f32_e32 v239, v192, v192
	v_fmac_f32_e32 v239, v193, v193
	v_fmac_f32_e32 v239, v194, v194
	v_fmac_f32_e32 v239, v195, v195
	v_fmac_f32_e32 v239, v196, v196
	v_fmac_f32_e32 v239, v197, v197
	v_fmac_f32_e32 v239, v198, v198
	v_fmac_f32_e32 v239, v199, v199
	v_cvt_pk_bf16_f32 v200, v200, v201
	v_cvt_pk_bf16_f32 v201, v202, v203
	v_cvt_pk_bf16_f32 v202, v204, v205
	v_cvt_pk_bf16_f32 v203, v206, v207
	global_store_dwordx4 v134, v[200:203], s[10:11]
	s_waitcnt vmcnt(20)
	v_lshlrev_b32_e32 v192, 16, v228
	v_and_b32_e32 v193, 0xffff0000, v228
	v_lshlrev_b32_e32 v194, 16, v229
	v_and_b32_e32 v195, 0xffff0000, v229
	v_lshlrev_b32_e32 v196, 16, v230
	v_and_b32_e32 v197, 0xffff0000, v230
	v_lshlrev_b32_e32 v198, 16, v231
	v_and_b32_e32 v199, 0xffff0000, v231
	v_fmac_f32_e32 v192, v160, v84
	v_fmac_f32_e32 v193, v161, v85
	v_fmac_f32_e32 v194, v162, v86
	v_fmac_f32_e32 v195, v163, v87
	v_fmac_f32_e32 v196, v164, v80
	v_fmac_f32_e32 v197, v165, v81
	v_fmac_f32_e32 v198, v166, v82
	v_fmac_f32_e32 v199, v167, v83
	v_cvt_pk_bf16_f32 v248, v192, v193
	v_cvt_pk_bf16_f32 v249, v194, v195
	v_cvt_pk_bf16_f32 v250, v196, v197
	v_cvt_pk_bf16_f32 v251, v198, v199
	global_store_dwordx4 v134, v[248:251], s[94:95] offset:256
	v_mul_f32_e32 v200, v192, v176
	v_mul_f32_e32 v201, v193, v177
	v_mul_f32_e32 v202, v194, v178
	v_mul_f32_e32 v203, v195, v179
	v_mul_f32_e32 v204, v196, v180
	v_mul_f32_e32 v205, v197, v181
	v_mul_f32_e32 v206, v198, v182
	v_mul_f32_e32 v207, v199, v183
	v_fmac_f32_e32 v239, v192, v192
	v_fmac_f32_e32 v239, v193, v193
	v_fmac_f32_e32 v239, v194, v194
	v_fmac_f32_e32 v239, v195, v195
	v_fmac_f32_e32 v239, v196, v196
	v_fmac_f32_e32 v239, v197, v197
	v_fmac_f32_e32 v239, v198, v198
	v_fmac_f32_e32 v239, v199, v199
	v_cvt_pk_bf16_f32 v200, v200, v201
	v_cvt_pk_bf16_f32 v201, v202, v203
	v_cvt_pk_bf16_f32 v202, v204, v205
	v_cvt_pk_bf16_f32 v203, v206, v207
	global_store_dwordx4 v134, v[200:203], s[10:11] offset:256
	s_waitcnt vmcnt(21)
	v_lshlrev_b32_e32 v192, 16, v232
	v_and_b32_e32 v193, 0xffff0000, v232
	v_lshlrev_b32_e32 v194, 16, v233
	v_and_b32_e32 v195, 0xffff0000, v233
	v_lshlrev_b32_e32 v196, 16, v234
	v_and_b32_e32 v197, 0xffff0000, v234
	v_lshlrev_b32_e32 v198, 16, v235
	v_and_b32_e32 v199, 0xffff0000, v235
	v_fmac_f32_e32 v192, v152, v76
	v_fmac_f32_e32 v193, v153, v77
	v_fmac_f32_e32 v194, v154, v78
	v_fmac_f32_e32 v195, v155, v79
	v_fmac_f32_e32 v196, v156, v72
	v_fmac_f32_e32 v197, v157, v73
	v_fmac_f32_e32 v198, v158, v74
	v_fmac_f32_e32 v199, v159, v75
	v_cvt_pk_bf16_f32 v248, v192, v193
	v_cvt_pk_bf16_f32 v249, v194, v195
	v_cvt_pk_bf16_f32 v250, v196, v197
	v_cvt_pk_bf16_f32 v251, v198, v199
	global_store_dwordx4 v135, v[248:251], s[94:95]
	v_mul_f32_e32 v200, v192, v168
	v_mul_f32_e32 v201, v193, v169
	v_mul_f32_e32 v202, v194, v170
	v_mul_f32_e32 v203, v195, v171
	v_mul_f32_e32 v204, v196, v172
	v_mul_f32_e32 v205, v197, v173
	v_mul_f32_e32 v206, v198, v174
	v_mul_f32_e32 v207, v199, v175
	v_mul_f32_e32 v240, v192, v192
	v_fmac_f32_e32 v240, v193, v193
	v_fmac_f32_e32 v240, v194, v194
	v_fmac_f32_e32 v240, v195, v195
	v_fmac_f32_e32 v240, v196, v196
	v_fmac_f32_e32 v240, v197, v197
	v_fmac_f32_e32 v240, v198, v198
	v_fmac_f32_e32 v240, v199, v199
	v_cvt_pk_bf16_f32 v200, v200, v201
	v_cvt_pk_bf16_f32 v201, v202, v203
	v_cvt_pk_bf16_f32 v202, v204, v205
	v_cvt_pk_bf16_f32 v203, v206, v207
	global_store_dwordx4 v135, v[200:203], s[10:11]
	s_waitcnt vmcnt(22)
	v_lshlrev_b32_e32 v192, 16, v128
	v_and_b32_e32 v193, 0xffff0000, v128
	v_lshlrev_b32_e32 v194, 16, v129
	v_and_b32_e32 v195, 0xffff0000, v129
	v_lshlrev_b32_e32 v196, 16, v130
	v_and_b32_e32 v197, 0xffff0000, v130
	v_lshlrev_b32_e32 v198, 16, v131
	v_and_b32_e32 v199, 0xffff0000, v131
	v_fmac_f32_e32 v192, v160, v68
	v_fmac_f32_e32 v193, v161, v69
	v_fmac_f32_e32 v194, v162, v70
	v_fmac_f32_e32 v195, v163, v71
	v_fmac_f32_e32 v196, v164, v64
	v_fmac_f32_e32 v197, v165, v65
	v_fmac_f32_e32 v198, v166, v66
	v_fmac_f32_e32 v199, v167, v67
	v_cvt_pk_bf16_f32 v248, v192, v193
	v_cvt_pk_bf16_f32 v249, v194, v195
	v_cvt_pk_bf16_f32 v250, v196, v197
	v_cvt_pk_bf16_f32 v251, v198, v199
	global_store_dwordx4 v135, v[248:251], s[94:95] offset:256
	v_mul_f32_e32 v200, v192, v176
	v_mul_f32_e32 v201, v193, v177
	v_mul_f32_e32 v202, v194, v178
	v_mul_f32_e32 v203, v195, v179
	v_mul_f32_e32 v204, v196, v180
	v_mul_f32_e32 v205, v197, v181
	v_mul_f32_e32 v206, v198, v182
	v_mul_f32_e32 v207, v199, v183
	v_fmac_f32_e32 v240, v192, v192
	v_fmac_f32_e32 v240, v193, v193
	v_fmac_f32_e32 v240, v194, v194
	v_fmac_f32_e32 v240, v195, v195
	v_fmac_f32_e32 v240, v196, v196
	v_fmac_f32_e32 v240, v197, v197
	v_fmac_f32_e32 v240, v198, v198
	v_fmac_f32_e32 v240, v199, v199
	v_cvt_pk_bf16_f32 v200, v200, v201
	v_cvt_pk_bf16_f32 v201, v202, v203
	v_cvt_pk_bf16_f32 v202, v204, v205
	v_cvt_pk_bf16_f32 v203, v206, v207
	global_store_dwordx4 v135, v[200:203], s[10:11] offset:256
	v_add_u32_e32 v253, 0x40000, v132
	s_waitcnt vmcnt(19)
	v_lshlrev_b32_e32 v192, 16, v124
	v_and_b32_e32 v193, 0xffff0000, v124
	v_lshlrev_b32_e32 v194, 16, v125
	v_and_b32_e32 v195, 0xffff0000, v125
	v_lshlrev_b32_e32 v196, 16, v126
	v_and_b32_e32 v197, 0xffff0000, v126
	v_lshlrev_b32_e32 v198, 16, v127
	v_and_b32_e32 v199, 0xffff0000, v127
	v_fmac_f32_e32 v192, v152, v60
	v_fmac_f32_e32 v193, v153, v61
	v_fmac_f32_e32 v194, v154, v62
	v_fmac_f32_e32 v195, v155, v63
	v_fmac_f32_e32 v196, v156, v56
	v_fmac_f32_e32 v197, v157, v57
	v_fmac_f32_e32 v198, v158, v58
	v_fmac_f32_e32 v199, v159, v59
	v_cvt_pk_bf16_f32 v248, v192, v193
	v_cvt_pk_bf16_f32 v249, v194, v195
	v_cvt_pk_bf16_f32 v250, v196, v197
	v_cvt_pk_bf16_f32 v251, v198, v199
	global_store_dwordx4 v253, v[248:251], s[94:95]
	v_mul_f32_e32 v200, v192, v168
	v_mul_f32_e32 v201, v193, v169
	v_mul_f32_e32 v202, v194, v170
	v_mul_f32_e32 v203, v195, v171
	v_mul_f32_e32 v204, v196, v172
	v_mul_f32_e32 v205, v197, v173
	v_mul_f32_e32 v206, v198, v174
	v_mul_f32_e32 v207, v199, v175
	v_mul_f32_e32 v241, v192, v192
	v_fmac_f32_e32 v241, v193, v193
	v_fmac_f32_e32 v241, v194, v194
	v_fmac_f32_e32 v241, v195, v195
	v_fmac_f32_e32 v241, v196, v196
	v_fmac_f32_e32 v241, v197, v197
	v_fmac_f32_e32 v241, v198, v198
	v_fmac_f32_e32 v241, v199, v199
	v_cvt_pk_bf16_f32 v200, v200, v201
	v_cvt_pk_bf16_f32 v201, v202, v203
	v_cvt_pk_bf16_f32 v202, v204, v205
	v_cvt_pk_bf16_f32 v203, v206, v207
	global_store_dwordx4 v253, v[200:203], s[10:11]
	s_waitcnt vmcnt(20)
	v_lshlrev_b32_e32 v192, 16, v120
	v_and_b32_e32 v193, 0xffff0000, v120
	v_lshlrev_b32_e32 v194, 16, v121
	v_and_b32_e32 v195, 0xffff0000, v121
	v_lshlrev_b32_e32 v196, 16, v122
	v_and_b32_e32 v197, 0xffff0000, v122
	v_lshlrev_b32_e32 v198, 16, v123
	v_and_b32_e32 v199, 0xffff0000, v123
	v_fmac_f32_e32 v192, v160, v52
	v_fmac_f32_e32 v193, v161, v53
	v_fmac_f32_e32 v194, v162, v54
	v_fmac_f32_e32 v195, v163, v55
	v_fmac_f32_e32 v196, v164, v48
	v_fmac_f32_e32 v197, v165, v49
	v_fmac_f32_e32 v198, v166, v50
	v_fmac_f32_e32 v199, v167, v51
	v_cvt_pk_bf16_f32 v248, v192, v193
	v_cvt_pk_bf16_f32 v249, v194, v195
	v_cvt_pk_bf16_f32 v250, v196, v197
	v_cvt_pk_bf16_f32 v251, v198, v199
	global_store_dwordx4 v253, v[248:251], s[94:95] offset:256
	v_mul_f32_e32 v200, v192, v176
	v_mul_f32_e32 v201, v193, v177
	v_mul_f32_e32 v202, v194, v178
	v_mul_f32_e32 v203, v195, v179
	v_mul_f32_e32 v204, v196, v180
	v_mul_f32_e32 v205, v197, v181
	v_mul_f32_e32 v206, v198, v182
	v_mul_f32_e32 v207, v199, v183
	v_fmac_f32_e32 v241, v192, v192
	v_fmac_f32_e32 v241, v193, v193
	v_fmac_f32_e32 v241, v194, v194
	v_fmac_f32_e32 v241, v195, v195
	v_fmac_f32_e32 v241, v196, v196
	v_fmac_f32_e32 v241, v197, v197
	v_fmac_f32_e32 v241, v198, v198
	v_fmac_f32_e32 v241, v199, v199
	v_cvt_pk_bf16_f32 v200, v200, v201
	v_cvt_pk_bf16_f32 v201, v202, v203
	v_cvt_pk_bf16_f32 v202, v204, v205
	v_cvt_pk_bf16_f32 v203, v206, v207
	global_store_dwordx4 v253, v[200:203], s[10:11] offset:256
	v_add_u32_e32 v253, 0x40000, v133
	s_waitcnt vmcnt(21)
	v_lshlrev_b32_e32 v192, 16, v116
	v_and_b32_e32 v193, 0xffff0000, v116
	v_lshlrev_b32_e32 v194, 16, v117
	v_and_b32_e32 v195, 0xffff0000, v117
	v_lshlrev_b32_e32 v196, 16, v118
	v_and_b32_e32 v197, 0xffff0000, v118
	v_lshlrev_b32_e32 v198, 16, v119
	v_and_b32_e32 v199, 0xffff0000, v119
	v_fmac_f32_e32 v192, v152, v44
	v_fmac_f32_e32 v193, v153, v45
	v_fmac_f32_e32 v194, v154, v46
	v_fmac_f32_e32 v195, v155, v47
	v_fmac_f32_e32 v196, v156, v40
	v_fmac_f32_e32 v197, v157, v41
	v_fmac_f32_e32 v198, v158, v42
	v_fmac_f32_e32 v199, v159, v43
	v_cvt_pk_bf16_f32 v248, v192, v193
	v_cvt_pk_bf16_f32 v249, v194, v195
	v_cvt_pk_bf16_f32 v250, v196, v197
	v_cvt_pk_bf16_f32 v251, v198, v199
	global_store_dwordx4 v253, v[248:251], s[94:95]
	v_mul_f32_e32 v200, v192, v168
	v_mul_f32_e32 v201, v193, v169
	v_mul_f32_e32 v202, v194, v170
	v_mul_f32_e32 v203, v195, v171
	v_mul_f32_e32 v204, v196, v172
	v_mul_f32_e32 v205, v197, v173
	v_mul_f32_e32 v206, v198, v174
	v_mul_f32_e32 v207, v199, v175
	v_mul_f32_e32 v242, v192, v192
	v_fmac_f32_e32 v242, v193, v193
	v_fmac_f32_e32 v242, v194, v194
	v_fmac_f32_e32 v242, v195, v195
	v_fmac_f32_e32 v242, v196, v196
	v_fmac_f32_e32 v242, v197, v197
	v_fmac_f32_e32 v242, v198, v198
	v_fmac_f32_e32 v242, v199, v199
	v_cvt_pk_bf16_f32 v200, v200, v201
	v_cvt_pk_bf16_f32 v201, v202, v203
	v_cvt_pk_bf16_f32 v202, v204, v205
	v_cvt_pk_bf16_f32 v203, v206, v207
	global_store_dwordx4 v253, v[200:203], s[10:11]
	s_waitcnt vmcnt(22)
	v_lshlrev_b32_e32 v192, 16, v112
	v_and_b32_e32 v193, 0xffff0000, v112
	v_lshlrev_b32_e32 v194, 16, v113
	v_and_b32_e32 v195, 0xffff0000, v113
	v_lshlrev_b32_e32 v196, 16, v114
	v_and_b32_e32 v197, 0xffff0000, v114
	v_lshlrev_b32_e32 v198, 16, v115
	v_and_b32_e32 v199, 0xffff0000, v115
	v_fmac_f32_e32 v192, v160, v36
	v_fmac_f32_e32 v193, v161, v37
	v_fmac_f32_e32 v194, v162, v38
	v_fmac_f32_e32 v195, v163, v39
	v_fmac_f32_e32 v196, v164, v32
	v_fmac_f32_e32 v197, v165, v33
	v_fmac_f32_e32 v198, v166, v34
	v_fmac_f32_e32 v199, v167, v35
	v_cvt_pk_bf16_f32 v248, v192, v193
	v_cvt_pk_bf16_f32 v249, v194, v195
	v_cvt_pk_bf16_f32 v250, v196, v197
	v_cvt_pk_bf16_f32 v251, v198, v199
	global_store_dwordx4 v253, v[248:251], s[94:95] offset:256
	v_mul_f32_e32 v200, v192, v176
	v_mul_f32_e32 v201, v193, v177
	v_mul_f32_e32 v202, v194, v178
	v_mul_f32_e32 v203, v195, v179
	v_mul_f32_e32 v204, v196, v180
	v_mul_f32_e32 v205, v197, v181
	v_mul_f32_e32 v206, v198, v182
	v_mul_f32_e32 v207, v199, v183
	v_fmac_f32_e32 v242, v192, v192
	v_fmac_f32_e32 v242, v193, v193
	v_fmac_f32_e32 v242, v194, v194
	v_fmac_f32_e32 v242, v195, v195
	v_fmac_f32_e32 v242, v196, v196
	v_fmac_f32_e32 v242, v197, v197
	v_fmac_f32_e32 v242, v198, v198
	v_fmac_f32_e32 v242, v199, v199
	v_cvt_pk_bf16_f32 v200, v200, v201
	v_cvt_pk_bf16_f32 v201, v202, v203
	v_cvt_pk_bf16_f32 v202, v204, v205
	v_cvt_pk_bf16_f32 v203, v206, v207
	global_store_dwordx4 v253, v[200:203], s[10:11] offset:256
	v_add_u32_e32 v253, 0x40000, v134
	s_waitcnt vmcnt(19)
	v_lshlrev_b32_e32 v192, 16, v108
	v_and_b32_e32 v193, 0xffff0000, v108
	v_lshlrev_b32_e32 v194, 16, v109
	v_and_b32_e32 v195, 0xffff0000, v109
	v_lshlrev_b32_e32 v196, 16, v110
	v_and_b32_e32 v197, 0xffff0000, v110
	v_lshlrev_b32_e32 v198, 16, v111
	v_and_b32_e32 v199, 0xffff0000, v111
	v_fmac_f32_e32 v192, v152, v28
	v_fmac_f32_e32 v193, v153, v29
	v_fmac_f32_e32 v194, v154, v30
	v_fmac_f32_e32 v195, v155, v31
	v_fmac_f32_e32 v196, v156, v24
	v_fmac_f32_e32 v197, v157, v25
	v_fmac_f32_e32 v198, v158, v26
	v_fmac_f32_e32 v199, v159, v27
	v_cvt_pk_bf16_f32 v248, v192, v193
	v_cvt_pk_bf16_f32 v249, v194, v195
	v_cvt_pk_bf16_f32 v250, v196, v197
	v_cvt_pk_bf16_f32 v251, v198, v199
	global_store_dwordx4 v253, v[248:251], s[94:95]
	v_mul_f32_e32 v200, v192, v168
	v_mul_f32_e32 v201, v193, v169
	v_mul_f32_e32 v202, v194, v170
	v_mul_f32_e32 v203, v195, v171
	v_mul_f32_e32 v204, v196, v172
	v_mul_f32_e32 v205, v197, v173
	v_mul_f32_e32 v206, v198, v174
	v_mul_f32_e32 v207, v199, v175
	v_mul_f32_e32 v243, v192, v192
	v_fmac_f32_e32 v243, v193, v193
	v_fmac_f32_e32 v243, v194, v194
	v_fmac_f32_e32 v243, v195, v195
	v_fmac_f32_e32 v243, v196, v196
	v_fmac_f32_e32 v243, v197, v197
	v_fmac_f32_e32 v243, v198, v198
	v_fmac_f32_e32 v243, v199, v199
	v_cvt_pk_bf16_f32 v200, v200, v201
	v_cvt_pk_bf16_f32 v201, v202, v203
	v_cvt_pk_bf16_f32 v202, v204, v205
	v_cvt_pk_bf16_f32 v203, v206, v207
	global_store_dwordx4 v253, v[200:203], s[10:11]
	s_waitcnt vmcnt(20)
	v_lshlrev_b32_e32 v192, 16, v104
	v_and_b32_e32 v193, 0xffff0000, v104
	v_lshlrev_b32_e32 v194, 16, v105
	v_and_b32_e32 v195, 0xffff0000, v105
	v_lshlrev_b32_e32 v196, 16, v106
	v_and_b32_e32 v197, 0xffff0000, v106
	v_lshlrev_b32_e32 v198, 16, v107
	v_and_b32_e32 v199, 0xffff0000, v107
	v_fmac_f32_e32 v192, v160, v20
	v_fmac_f32_e32 v193, v161, v21
	v_fmac_f32_e32 v194, v162, v22
	v_fmac_f32_e32 v195, v163, v23
	v_fmac_f32_e32 v196, v164, v16
	v_fmac_f32_e32 v197, v165, v17
	v_fmac_f32_e32 v198, v166, v18
	v_fmac_f32_e32 v199, v167, v19
	v_cvt_pk_bf16_f32 v248, v192, v193
	v_cvt_pk_bf16_f32 v249, v194, v195
	v_cvt_pk_bf16_f32 v250, v196, v197
	v_cvt_pk_bf16_f32 v251, v198, v199
	global_store_dwordx4 v253, v[248:251], s[94:95] offset:256
	v_mul_f32_e32 v200, v192, v176
	v_mul_f32_e32 v201, v193, v177
	v_mul_f32_e32 v202, v194, v178
	v_mul_f32_e32 v203, v195, v179
	v_mul_f32_e32 v204, v196, v180
	v_mul_f32_e32 v205, v197, v181
	v_mul_f32_e32 v206, v198, v182
	v_mul_f32_e32 v207, v199, v183
	v_fmac_f32_e32 v243, v192, v192
	v_fmac_f32_e32 v243, v193, v193
	v_fmac_f32_e32 v243, v194, v194
	v_fmac_f32_e32 v243, v195, v195
	v_fmac_f32_e32 v243, v196, v196
	v_fmac_f32_e32 v243, v197, v197
	v_fmac_f32_e32 v243, v198, v198
	v_fmac_f32_e32 v243, v199, v199
	v_cvt_pk_bf16_f32 v200, v200, v201
	v_cvt_pk_bf16_f32 v201, v202, v203
	v_cvt_pk_bf16_f32 v202, v204, v205
	v_cvt_pk_bf16_f32 v203, v206, v207
	global_store_dwordx4 v253, v[200:203], s[10:11] offset:256
	v_add_u32_e32 v253, 0x40000, v135
	s_waitcnt vmcnt(21)
	v_lshlrev_b32_e32 v192, 16, v100
	v_and_b32_e32 v193, 0xffff0000, v100
	v_lshlrev_b32_e32 v194, 16, v101
	v_and_b32_e32 v195, 0xffff0000, v101
	v_lshlrev_b32_e32 v196, 16, v102
	v_and_b32_e32 v197, 0xffff0000, v102
	v_lshlrev_b32_e32 v198, 16, v103
	v_and_b32_e32 v199, 0xffff0000, v103
	v_fmac_f32_e32 v192, v152, v12
	v_fmac_f32_e32 v193, v153, v13
	v_fmac_f32_e32 v194, v154, v14
	v_fmac_f32_e32 v195, v155, v15
	v_fmac_f32_e32 v196, v156, v8
	v_fmac_f32_e32 v197, v157, v9
	v_fmac_f32_e32 v198, v158, v10
	v_fmac_f32_e32 v199, v159, v11
	v_cvt_pk_bf16_f32 v248, v192, v193
	v_cvt_pk_bf16_f32 v249, v194, v195
	v_cvt_pk_bf16_f32 v250, v196, v197
	v_cvt_pk_bf16_f32 v251, v198, v199
	global_store_dwordx4 v253, v[248:251], s[94:95]
	v_mul_f32_e32 v200, v192, v168
	v_mul_f32_e32 v201, v193, v169
	v_mul_f32_e32 v202, v194, v170
	v_mul_f32_e32 v203, v195, v171
	v_mul_f32_e32 v204, v196, v172
	v_mul_f32_e32 v205, v197, v173
	v_mul_f32_e32 v206, v198, v174
	v_mul_f32_e32 v207, v199, v175
	v_mul_f32_e32 v244, v192, v192
	v_fmac_f32_e32 v244, v193, v193
	v_fmac_f32_e32 v244, v194, v194
	v_fmac_f32_e32 v244, v195, v195
	v_fmac_f32_e32 v244, v196, v196
	v_fmac_f32_e32 v244, v197, v197
	v_fmac_f32_e32 v244, v198, v198
	v_fmac_f32_e32 v244, v199, v199
	v_cvt_pk_bf16_f32 v200, v200, v201
	v_cvt_pk_bf16_f32 v201, v202, v203
	v_cvt_pk_bf16_f32 v202, v204, v205
	v_cvt_pk_bf16_f32 v203, v206, v207
	global_store_dwordx4 v253, v[200:203], s[10:11]
	s_waitcnt vmcnt(22)
	v_lshlrev_b32_e32 v192, 16, v96
	v_and_b32_e32 v193, 0xffff0000, v96
	v_lshlrev_b32_e32 v194, 16, v97
	v_and_b32_e32 v195, 0xffff0000, v97
	v_lshlrev_b32_e32 v196, 16, v98
	v_and_b32_e32 v197, 0xffff0000, v98
	v_lshlrev_b32_e32 v198, 16, v99
	v_and_b32_e32 v199, 0xffff0000, v99
	v_fmac_f32_e32 v192, v160, v4
	v_fmac_f32_e32 v193, v161, v5
	v_fmac_f32_e32 v194, v162, v6
	v_fmac_f32_e32 v195, v163, v7
	v_fmac_f32_e32 v196, v164, v0
	v_fmac_f32_e32 v197, v165, v1
	v_fmac_f32_e32 v198, v166, v2
	v_fmac_f32_e32 v199, v167, v3
	v_cvt_pk_bf16_f32 v248, v192, v193
	v_cvt_pk_bf16_f32 v249, v194, v195
	v_cvt_pk_bf16_f32 v250, v196, v197
	v_cvt_pk_bf16_f32 v251, v198, v199
	global_store_dwordx4 v253, v[248:251], s[94:95] offset:256
	v_mul_f32_e32 v200, v192, v176
	v_mul_f32_e32 v201, v193, v177
	v_mul_f32_e32 v202, v194, v178
	v_mul_f32_e32 v203, v195, v179
	v_mul_f32_e32 v204, v196, v180
	v_mul_f32_e32 v205, v197, v181
	v_mul_f32_e32 v206, v198, v182
	v_mul_f32_e32 v207, v199, v183
	v_fmac_f32_e32 v244, v192, v192
	v_fmac_f32_e32 v244, v193, v193
	v_fmac_f32_e32 v244, v194, v194
	v_fmac_f32_e32 v244, v195, v195
	v_fmac_f32_e32 v244, v196, v196
	v_fmac_f32_e32 v244, v197, v197
	v_fmac_f32_e32 v244, v198, v198
	v_fmac_f32_e32 v244, v199, v199
	v_cvt_pk_bf16_f32 v200, v200, v201
	v_cvt_pk_bf16_f32 v201, v202, v203
	v_cvt_pk_bf16_f32 v202, v204, v205
	v_cvt_pk_bf16_f32 v203, v206, v207
	global_store_dwordx4 v253, v[200:203], s[10:11] offset:256
	v_and_b32_e32 v252, 63, v236
	v_xor_b32_e32 v246, 16, v252
	v_lshlrev_b32_e32 v246, 2, v246
	v_xor_b32_e32 v247, 32, v252
	v_lshlrev_b32_e32 v247, 2, v247
	ds_bpermute_b32 v192, v246, v237
	ds_bpermute_b32 v193, v246, v238
	ds_bpermute_b32 v194, v246, v239
	ds_bpermute_b32 v195, v246, v240
	ds_bpermute_b32 v196, v246, v241
	ds_bpermute_b32 v197, v246, v242
	ds_bpermute_b32 v198, v246, v243
	ds_bpermute_b32 v199, v246, v244
	s_waitcnt lgkmcnt(7)
	v_add_f32_e32 v237, v237, v192
	s_waitcnt lgkmcnt(6)
	v_add_f32_e32 v238, v238, v193
	s_waitcnt lgkmcnt(5)
	v_add_f32_e32 v239, v239, v194
	s_waitcnt lgkmcnt(4)
	v_add_f32_e32 v240, v240, v195
	s_waitcnt lgkmcnt(3)
	v_add_f32_e32 v241, v241, v196
	s_waitcnt lgkmcnt(2)
	v_add_f32_e32 v242, v242, v197
	s_waitcnt lgkmcnt(1)
	v_add_f32_e32 v243, v243, v198
	s_waitcnt lgkmcnt(0)
	v_add_f32_e32 v244, v244, v199
	ds_bpermute_b32 v192, v247, v237
	ds_bpermute_b32 v193, v247, v238
	ds_bpermute_b32 v194, v247, v239
	ds_bpermute_b32 v195, v247, v240
	ds_bpermute_b32 v196, v247, v241
	ds_bpermute_b32 v197, v247, v242
	ds_bpermute_b32 v198, v247, v243
	ds_bpermute_b32 v199, v247, v244
	s_waitcnt lgkmcnt(7)
	v_add_f32_e32 v237, v237, v192
	s_waitcnt lgkmcnt(6)
	v_add_f32_e32 v238, v238, v193
	s_waitcnt lgkmcnt(5)
	v_add_f32_e32 v239, v239, v194
	s_waitcnt lgkmcnt(4)
	v_add_f32_e32 v240, v240, v195
	s_waitcnt lgkmcnt(3)
	v_add_f32_e32 v241, v241, v196
	s_waitcnt lgkmcnt(2)
	v_add_f32_e32 v242, v242, v197
	s_waitcnt lgkmcnt(1)
	v_add_f32_e32 v243, v243, v198
	s_waitcnt lgkmcnt(0)
	v_add_f32_e32 v244, v244, v199
	s_and_saveexec_b64 s[28:29], s[0:1]
	global_atomic_add_f32 v245, v237, s[14:15] offset:0
	global_atomic_add_f32 v245, v238, s[14:15] offset:64
	global_atomic_add_f32 v245, v239, s[14:15] offset:128
	global_atomic_add_f32 v245, v240, s[14:15] offset:192
	global_atomic_add_f32 v245, v241, s[14:15] offset:512
	global_atomic_add_f32 v245, v242, s[14:15] offset:576
	global_atomic_add_f32 v245, v243, s[14:15] offset:640
	global_atomic_add_f32 v245, v244, s[14:15] offset:704
	s_or_b64 exec, exec, s[28:29]
	s_andn2_b64 vcc, exec, s[6:7]
	s_mov_b64 s[6:7], -1
	s_cbranch_vccnz .LBB0_1018
	s_andn2_b64 vcc, exec, s[8:9]
	s_cbranch_vccnz .LBB0_1017
	s_barrier
	s_branch .LBB0_1017
